# PZ1: attention: the 8 per-tile permlane32_swap of the packed P operand removed (V tile key rows stored un-permuted in LDS instead), on top of Y1
# speedup vs baseline: 1.0163x; 1.0007x over previous
.LBB0_626:
	v_mov_b32_e32 v4, v0
	s_lshl_b64 s[8:9], s[18:19], 12
	s_add_u32 s8, s4, s8
	v_ashrrev_i32_e32 v167, 6, v4
	v_and_b32_e32 v165, 31, v4
	v_lshlrev_b32_e32 v164, 5, v167
	s_addc_u32 s9, s5, s9
	s_lshl_b32 s18, s30, 8
	v_or_b32_e32 v6, v164, v165
	s_add_u32 s40, s8, s18
	v_ashrrev_i32_e32 v7, 31, v6
	s_addc_u32 s41, s9, 0
	v_bfe_u32 v170, v4, 5, 1
	v_lshlrev_b64 v[6:7], 12, v[6:7]
	v_lshl_add_u64 v[6:7], s[40:41], 0, v[6:7]
	v_lshlrev_b32_e32 v168, 4, v170
	v_mov_b32_e32 v169, v3
	s_lshl_b64 s[8:9], s[16:17], 10
	v_lshl_add_u64 v[6:7], v[6:7], 0, v[168:169]
	v_ashrrev_i32_e32 v5, 4, v4
	s_add_u32 s18, s14, s8
	global_load_dwordx4 v[128:131], v[6:7], off
	global_load_dwordx4 v[124:127], v[6:7], off offset:32
	global_load_dwordx4 v[120:123], v[6:7], off offset:64
	global_load_dwordx4 v[116:119], v[6:7], off offset:96
	global_load_dwordx4 v[112:115], v[6:7], off offset:128
	global_load_dwordx4 v[108:111], v[6:7], off offset:160
	global_load_dwordx4 v[104:107], v[6:7], off offset:192
	global_load_dwordx4 v[100:103], v[6:7], off offset:224
	v_and_b32_e32 v7, 0xfffff8, v5
	v_lshlrev_b32_e32 v8, 1, v5
	s_addc_u32 s19, s15, s9
	s_lshl_b64 s[16:17], s[36:37], 1
	v_lshrrev_b32_e32 v8, 1, v5
	v_and_b32_e32 v9, 3, v5
	v_add_u32_e32 v22, 32, v5
	s_add_u32 s30, s18, s16
	v_and_b32_e32 v8, 7, v5
	v_and_b32_e32 v9, 0xfffff8, v22
	v_lshlrev_b32_e32 v10, 1, v22
	s_addc_u32 s31, s19, s17
	v_lshlrev_b32_e32 v2, 3, v4
	s_add_u32 s8, s28, s8
	v_and_b32_e32 v6, 0x78, v2
	v_lshrrev_b32_e32 v7, 1, v7
	v_bfe_u32 v2, v2, 5, 2
	v_lshrrev_b32_e32 v9, 1, v9
	s_addc_u32 s9, s29, s9
	v_or_b32_e32 v7, v7, v2
	v_lshlrev_b32_e32 v166, 1, v6
	v_or_b32_e32 v2, v9, v2
	s_add_u32 s42, s8, s16
	v_lshlrev_b32_e32 v8, 6, v8
	v_and_b32_e32 v6, 48, v166
	v_lshlrev_b32_e32 v2, 9, v2
	s_addc_u32 s43, s9, s17
	v_lshlrev_b32_e32 v7, 9, v7
	v_or3_b32 v178, v2, v8, v6
	v_lshl_or_b32 v2, v5, 10, v166
	v_or3_b32 v179, v7, v8, v6
	v_lshl_add_u64 v[36:37], s[42:43], 0, v[2:3]
	global_load_dwordx4 v[6:9], v2, s[42:43]
	global_load_dwordx4 v[14:17], v2, s[30:31]
	v_add_co_u32_e32 v10, vcc, s33, v36
	v_lshl_add_u64 v[38:39], s[30:31], 0, v[2:3]
	s_nop 0
	v_addc_co_u32_e32 v11, vcc, 0, v37, vcc
	global_load_dwordx4 v[10:13], v[10:11], off
	v_add_co_u32_e32 v18, vcc, s33, v38
	v_add_u32_e32 v40, 0, v179
	s_nop 0
	v_addc_co_u32_e32 v19, vcc, 0, v39, vcc
	global_load_dwordx4 v[18:21], v[18:19], off
	s_waitcnt vmcnt(0)
	v_lshlrev_b32_e32 v5, 8, v5
	v_add_u32_e32 v41, 0, v178
	s_mov_b32 s8, 0x10000
	v_readfirstlane_b32 s18, v4
	s_waitcnt vmcnt(0)
	ds_write_b128 v40, v[6:9]
	v_and_b32_e32 v6, 0x70, v4
	v_bitop3_b32 v180, v166, v5, v6 bitop3:0xde
	v_add_u32_e32 v5, 0, v180
	ds_write_b128 v41, v[10:13]
	ds_write_b128 v5, v[14:17] offset:49152
	v_lshlrev_b32_e32 v5, 8, v22
	v_bitop3_b32 v181, v166, v5, v6 bitop3:0xde
	v_add_co_u32_e32 v6, vcc, s8, v36
	v_add_u32_e32 v5, 0, v181
	s_nop 0
	v_addc_co_u32_e32 v7, vcc, 0, v37, vcc
	ds_write_b128 v5, v[18:21] offset:49152
	global_load_dwordx4 v[20:23], v[6:7], off
	v_add_co_u32_e32 v6, vcc, 0x18000, v36
	s_nop 1
	v_addc_co_u32_e32 v7, vcc, 0, v37, vcc
	global_load_dwordx4 v[24:27], v[6:7], off
	v_add_co_u32_e32 v6, vcc, 0x10000, v38
	s_nop 1
	v_addc_co_u32_e32 v7, vcc, 0, v39, vcc
	global_load_dwordx4 v[28:31], v[6:7], off
	v_add_co_u32_e32 v6, vcc, 0x18000, v38
	s_nop 1
	v_addc_co_u32_e32 v7, vcc, 0, v39, vcc
	global_load_dwordx4 v[32:35], v[6:7], off
	s_waitcnt lgkmcnt(0)
	s_barrier
	s_and_b32 s8, s18, 0xffffff00
	s_cmpk_lg_i32 s8, 0x100
	s_cbranch_scc1 .LBB0_628
	s_waitcnt lgkmcnt(0)
	s_barrier

.LBB0_629:
	v_max_f32_e32 v148, v84, v85
	v_max_f32_e32 v149, v68, v69
	v_max3_f32 v148, v148, v86, v87
	v_max3_f32 v149, v149, v70, v71
	v_max3_f32 v148, v148, v88, v89
	v_max3_f32 v149, v149, v72, v73
	v_max3_f32 v148, v148, v90, v91
	v_max3_f32 v149, v149, v74, v75
	v_max3_f32 v148, v148, v92, v93
	v_max3_f32 v149, v149, v76, v77
	v_max3_f32 v148, v148, v94, v95
	v_max3_f32 v149, v149, v78, v79
	v_max3_f32 v148, v148, v96, v97
	v_max3_f32 v149, v149, v80, v81
	v_max3_f32 v148, v148, v98, v99
	v_max3_f32 v149, v149, v82, v83
	v_max_f32_e32 v148, v148, v149
	v_mov_b32_e32 v149, v148
	s_nop 1
	v_permlane32_swap_b32_e32 v148, v149
	v_max_f32_e32 v148, v148, v149
	v_sub_f32_e32 v149, v148, v182
	v_cmp_ge_f32_e32 vcc, s23, v149
	v_max_f32_e32 v148, v182, v148
	s_cmp_eq_u64 vcc, exec
	s_cselect_b64 vcc, -1, 0
	v_sub_f32_e32 v150, v182, v148
	v_cndmask_b32_e32 v182, v148, v182, vcc
	v_mul_f32_e32 v148, 0xbe0293ee, v182
	v_fmamk_f32 v84, v84, 0x3e0293ee, v148
	v_fmamk_f32 v85, v85, 0x3e0293ee, v148
	v_fmamk_f32 v86, v86, 0x3e0293ee, v148
	v_fmamk_f32 v87, v87, 0x3e0293ee, v148
	v_fmamk_f32 v88, v88, 0x3e0293ee, v148
	v_fmamk_f32 v89, v89, 0x3e0293ee, v148
	v_fmamk_f32 v90, v90, 0x3e0293ee, v148
	v_fmamk_f32 v91, v91, 0x3e0293ee, v148
	v_fmamk_f32 v92, v92, 0x3e0293ee, v148
	v_fmamk_f32 v93, v93, 0x3e0293ee, v148
	v_fmamk_f32 v94, v94, 0x3e0293ee, v148
	v_fmamk_f32 v95, v95, 0x3e0293ee, v148
	v_fmamk_f32 v96, v96, 0x3e0293ee, v148
	v_fmamk_f32 v97, v97, 0x3e0293ee, v148
	v_fmamk_f32 v98, v98, 0x3e0293ee, v148
	v_fmamk_f32 v99, v99, 0x3e0293ee, v148
	v_fmamk_f32 v68, v68, 0x3e0293ee, v148
	v_fmamk_f32 v69, v69, 0x3e0293ee, v148
	v_fmamk_f32 v70, v70, 0x3e0293ee, v148
	v_fmamk_f32 v71, v71, 0x3e0293ee, v148
	v_fmamk_f32 v72, v72, 0x3e0293ee, v148
	v_fmamk_f32 v73, v73, 0x3e0293ee, v148
	v_fmamk_f32 v74, v74, 0x3e0293ee, v148
	v_fmamk_f32 v75, v75, 0x3e0293ee, v148
	v_fmamk_f32 v76, v76, 0x3e0293ee, v148
	v_fmamk_f32 v77, v77, 0x3e0293ee, v148
	v_fmamk_f32 v78, v78, 0x3e0293ee, v148
	v_fmamk_f32 v79, v79, 0x3e0293ee, v148
	v_fmamk_f32 v80, v80, 0x3e0293ee, v148
	v_fmamk_f32 v81, v81, 0x3e0293ee, v148
	v_fmamk_f32 v82, v82, 0x3e0293ee, v148
	v_fmac_f32_e32 v148, 0x3e0293ee, v83
	v_exp_f32_e32 v83, v84
	v_exp_f32_e32 v84, v85
	v_exp_f32_e32 v85, v86
	v_add_f32_e32 v149, v84, v83
	v_exp_f32_e32 v86, v87
	v_add_f32_e32 v149, v85, v149
	v_exp_f32_e32 v87, v88
	v_add_f32_e32 v149, v86, v149
	v_exp_f32_e32 v88, v89
	v_add_f32_e32 v149, v87, v149
	v_exp_f32_e32 v89, v90
	v_add_f32_e32 v149, v88, v149
	v_exp_f32_e32 v90, v91
	v_add_f32_e32 v149, v89, v149
	v_exp_f32_e32 v91, v92
	v_add_f32_e32 v149, v90, v149
	v_exp_f32_e32 v92, v93
	v_add_f32_e32 v149, v91, v149
	v_exp_f32_e32 v93, v94
	v_add_f32_e32 v149, v92, v149
	v_exp_f32_e32 v94, v95
	v_add_f32_e32 v149, v93, v149
	v_exp_f32_e32 v95, v96
	v_add_f32_e32 v149, v94, v149
	v_exp_f32_e32 v96, v97
	v_add_f32_e32 v149, v95, v149
	v_exp_f32_e32 v97, v98
	v_add_f32_e32 v149, v96, v149
	v_exp_f32_e32 v98, v99
	v_add_f32_e32 v149, v97, v149
	v_exp_f32_e32 v99, v148
	v_add_f32_e32 v149, v98, v149
	v_exp_f32_e32 v68, v68
	v_exp_f32_e32 v69, v69
	v_add_f32_e32 v149, v68, v149
	v_exp_f32_e32 v70, v70
	v_add_f32_e32 v149, v69, v149
	v_exp_f32_e32 v71, v71
	v_add_f32_e32 v149, v70, v149
	v_exp_f32_e32 v72, v72
	v_add_f32_e32 v149, v71, v149
	v_exp_f32_e32 v73, v73
	v_add_f32_e32 v149, v72, v149
	v_exp_f32_e32 v74, v74
	v_add_f32_e32 v149, v73, v149
	v_exp_f32_e32 v75, v75
	v_add_f32_e32 v149, v74, v149
	v_exp_f32_e32 v76, v76
	v_add_f32_e32 v149, v75, v149
	v_exp_f32_e32 v77, v77
	v_add_f32_e32 v149, v76, v149
	v_exp_f32_e32 v78, v78
	v_add_f32_e32 v149, v77, v149
	v_exp_f32_e32 v79, v79
	v_add_f32_e32 v149, v78, v149
	v_exp_f32_e32 v80, v80
	v_add_f32_e32 v149, v79, v149
	v_exp_f32_e32 v81, v81
	v_add_f32_e32 v149, v80, v149
	v_exp_f32_e32 v82, v82
	v_add_f32_e32 v149, v81, v149
	v_mul_f32_e32 v150, 0x3e0293ee, v150
	v_add_f32_e32 v149, v82, v149
	v_exp_f32_e32 v150, v150
	v_add_f32_e32 v185, v99, v149
	v_cndmask_b32_e64 v184, v150, 1.0, vcc
	v_mov_b32_e32 v186, v185
	v_cvt_pk_bf16_f32 v148, v83, v84
	v_cvt_pk_bf16_f32 v149, v85, v86
	v_cvt_pk_bf16_f32 v150, v87, v88
	v_cvt_pk_bf16_f32 v151, v89, v90
	v_cvt_pk_bf16_f32 v152, v91, v92
	v_cvt_pk_bf16_f32 v153, v93, v94
	v_cvt_pk_bf16_f32 v154, v95, v96
	v_cvt_pk_bf16_f32 v155, v97, v98
	v_cvt_pk_bf16_f32 v156, v68, v69
	v_cvt_pk_bf16_f32 v157, v70, v71
	v_cvt_pk_bf16_f32 v158, v72, v73
	v_cvt_pk_bf16_f32 v159, v74, v75
	v_cvt_pk_bf16_f32 v160, v76, v77
	v_cvt_pk_bf16_f32 v161, v78, v79
	v_cvt_pk_bf16_f32 v162, v80, v81
	v_cvt_pk_bf16_f32 v163, v82, v99
	s_mov_b32 s53, s52
	s_nop 0
	v_permlane32_swap_b32_e32 v185, v186
	v_cmp_gt_f32_e32 vcc, 1.0, v184
	s_cbranch_vccz .LBB0_633
	s_and_saveexec_b64 s[16:17], s[38:39]
	ds_write_b32 v172, v184 offset:128
	s_or_b64 exec, exec, s[16:17]
	s_waitcnt lgkmcnt(0)
	v_add_u32_e32 v80, v171, v168
	ds_read_b128 v[68:71], v80 offset:224
	ds_read_b128 v[72:75], v80 offset:192
	ds_read_b128 v[76:79], v80 offset:160
	ds_read_b128 v[80:83], v80 offset:128
	s_waitcnt lgkmcnt(3)
	v_pk_mul_f32 v[16:17], v[16:17], v[68:69]
	s_waitcnt lgkmcnt(2)
	v_pk_mul_f32 v[12:13], v[12:13], v[72:73]
	s_waitcnt lgkmcnt(1)
	v_pk_mul_f32 v[8:9], v[8:9], v[76:77]
	v_pk_mul_f32 v[18:19], v[18:19], v[70:71]
	v_pk_mul_f32 v[14:15], v[14:15], v[74:75]
	v_pk_mul_f32 v[10:11], v[10:11], v[78:79]
	s_waitcnt lgkmcnt(0)
	v_pk_mul_f32 v[6:7], v[6:7], v[82:83]
	v_pk_mul_f32 v[4:5], v[4:5], v[80:81]
	v_pk_mul_f32 v[64:65], v[64:65], v[68:69]
	v_pk_mul_f32 v[60:61], v[60:61], v[72:73]
	v_pk_mul_f32 v[56:57], v[56:57], v[76:77]
	v_pk_mul_f32 v[66:67], v[66:67], v[70:71]
	v_pk_mul_f32 v[62:63], v[62:63], v[74:75]
	v_pk_mul_f32 v[58:59], v[58:59], v[78:79]
	v_pk_mul_f32 v[54:55], v[54:55], v[82:83]
	v_pk_mul_f32 v[52:53], v[52:53], v[80:81]
	v_pk_mul_f32 v[48:49], v[48:49], v[68:69]
	v_pk_mul_f32 v[44:45], v[44:45], v[72:73]
	v_pk_mul_f32 v[40:41], v[40:41], v[76:77]
	v_pk_mul_f32 v[50:51], v[50:51], v[70:71]
	v_pk_mul_f32 v[46:47], v[46:47], v[74:75]
	v_pk_mul_f32 v[42:43], v[42:43], v[78:79]
	v_pk_mul_f32 v[38:39], v[38:39], v[82:83]
	v_pk_mul_f32 v[36:37], v[36:37], v[80:81]
	v_pk_mul_f32 v[32:33], v[32:33], v[68:69]
	v_pk_mul_f32 v[28:29], v[28:29], v[72:73]
	v_pk_mul_f32 v[24:25], v[24:25], v[76:77]
	v_pk_mul_f32 v[34:35], v[34:35], v[70:71]
	v_pk_mul_f32 v[30:31], v[30:31], v[74:75]
	v_pk_mul_f32 v[26:27], v[26:27], v[78:79]
	v_pk_mul_f32 v[22:23], v[22:23], v[82:83]
	v_pk_mul_f32 v[20:21], v[20:21], v[80:81]

.LBB0_637:
	v_max_f32_e32 v2, v85, v85
	s_waitcnt vmcnt(0)
	v_max_f32_e32 v132, v84, v84
	v_max_f32_e32 v2, v132, v2
	v_max3_f32 v2, v2, v86, v87
	v_max3_f32 v2, v2, v88, v89
	v_max3_f32 v2, v2, v90, v91
	v_max3_f32 v2, v2, v92, v93
	v_max3_f32 v2, v2, v94, v95
	v_max3_f32 v2, v2, v96, v97
	v_max3_f32 v2, v2, v98, v99
	v_max3_f32 v2, v2, v68, v69
	v_max3_f32 v2, v2, v70, v71
	v_max3_f32 v2, v2, v72, v73
	v_max3_f32 v2, v2, v74, v75
	v_max3_f32 v2, v2, v76, v77
	v_max3_f32 v2, v2, v78, v79
	v_max3_f32 v2, v2, v80, v81
	v_max3_f32 v2, v2, v82, v83
	v_mov_b32_e32 v132, v2
	s_nop 1
	v_permlane32_swap_b32_e32 v2, v132
	v_max_f32_e32 v132, v132, v132
	v_max_f32_e32 v2, v2, v2
	v_max_f32_e32 v2, v2, v132
	v_sub_f32_e32 v132, v2, v182
	v_cmp_ge_f32_e32 vcc, s23, v132
	v_max_f32_e32 v133, v182, v182
	s_cmp_eq_u64 vcc, exec
	v_max_f32_e32 v133, v133, v2
	s_cselect_b64 vcc, -1, 0
	v_cndmask_b32_e32 v151, v133, v182, vcc
	v_mul_f32_e32 v132, 0xbe0293ee, v151
	v_fmamk_f32 v84, v84, 0x3e0293ee, v132
	v_fmamk_f32 v85, v85, 0x3e0293ee, v132
	v_fmamk_f32 v86, v86, 0x3e0293ee, v132
	v_fmamk_f32 v87, v87, 0x3e0293ee, v132
	v_fmamk_f32 v88, v88, 0x3e0293ee, v132
	v_fmamk_f32 v89, v89, 0x3e0293ee, v132
	v_fmamk_f32 v90, v90, 0x3e0293ee, v132
	v_fmamk_f32 v91, v91, 0x3e0293ee, v132
	v_fmamk_f32 v92, v92, 0x3e0293ee, v132
	v_fmamk_f32 v93, v93, 0x3e0293ee, v132
	v_fmamk_f32 v94, v94, 0x3e0293ee, v132
	v_fmamk_f32 v95, v95, 0x3e0293ee, v132
	v_fmamk_f32 v96, v96, 0x3e0293ee, v132
	v_fmamk_f32 v97, v97, 0x3e0293ee, v132
	v_fmamk_f32 v98, v98, 0x3e0293ee, v132
	v_fmamk_f32 v99, v99, 0x3e0293ee, v132
	v_fmamk_f32 v68, v68, 0x3e0293ee, v132
	v_fmamk_f32 v69, v69, 0x3e0293ee, v132
	v_fmamk_f32 v70, v70, 0x3e0293ee, v132
	v_fmamk_f32 v71, v71, 0x3e0293ee, v132
	v_fmamk_f32 v72, v72, 0x3e0293ee, v132
	v_fmamk_f32 v73, v73, 0x3e0293ee, v132
	v_fmamk_f32 v74, v74, 0x3e0293ee, v132
	v_fmamk_f32 v75, v75, 0x3e0293ee, v132
	v_fmamk_f32 v76, v76, 0x3e0293ee, v132
	v_fmamk_f32 v77, v77, 0x3e0293ee, v132
	v_fmamk_f32 v78, v78, 0x3e0293ee, v132
	v_fmamk_f32 v79, v79, 0x3e0293ee, v132
	v_fmamk_f32 v80, v80, 0x3e0293ee, v132
	v_fmamk_f32 v81, v81, 0x3e0293ee, v132
	v_fmamk_f32 v82, v82, 0x3e0293ee, v132
	v_fmac_f32_e32 v132, 0x3e0293ee, v83
	v_exp_f32_e32 v83, v84
	v_exp_f32_e32 v84, v85
	v_exp_f32_e32 v85, v86
	v_exp_f32_e32 v86, v87
	v_exp_f32_e32 v87, v88
	v_exp_f32_e32 v88, v89
	v_exp_f32_e32 v89, v90
	v_exp_f32_e32 v90, v91
	v_exp_f32_e32 v91, v92
	v_exp_f32_e32 v92, v93
	v_exp_f32_e32 v93, v94
	v_exp_f32_e32 v94, v95
	v_exp_f32_e32 v95, v96
	v_exp_f32_e32 v96, v97
	v_exp_f32_e32 v97, v98
	v_exp_f32_e32 v98, v99
	v_exp_f32_e32 v99, v132
	v_add_f32_e32 v132, 0, v83
	v_add_f32_e32 v132, v84, v132
	v_add_f32_e32 v132, v85, v132
	v_add_f32_e32 v132, v86, v132
	v_add_f32_e32 v132, v87, v132
	v_add_f32_e32 v132, v88, v132
	v_add_f32_e32 v132, v89, v132
	v_add_f32_e32 v132, v90, v132
	v_add_f32_e32 v132, v91, v132
	v_add_f32_e32 v132, v92, v132
	v_add_f32_e32 v132, v93, v132
	v_add_f32_e32 v132, v94, v132
	v_exp_f32_e32 v68, v68
	v_add_f32_e32 v132, v95, v132
	v_exp_f32_e32 v69, v69
	v_add_f32_e32 v132, v96, v132
	v_exp_f32_e32 v70, v70
	v_add_f32_e32 v132, v97, v132
	v_exp_f32_e32 v71, v71
	v_add_f32_e32 v132, v98, v132
	v_exp_f32_e32 v72, v72
	v_add_f32_e32 v132, v68, v132
	v_exp_f32_e32 v73, v73
	v_add_f32_e32 v132, v69, v132
	v_exp_f32_e32 v74, v74
	v_add_f32_e32 v132, v70, v132
	v_exp_f32_e32 v75, v75
	v_add_f32_e32 v132, v71, v132
	v_exp_f32_e32 v76, v76
	v_add_f32_e32 v132, v72, v132
	v_exp_f32_e32 v77, v77
	v_add_f32_e32 v132, v73, v132
	v_exp_f32_e32 v78, v78
	v_add_f32_e32 v132, v74, v132
	v_exp_f32_e32 v79, v79
	v_add_f32_e32 v132, v75, v132
	v_exp_f32_e32 v80, v80
	v_add_f32_e32 v132, v76, v132
	v_exp_f32_e32 v81, v81
	v_add_f32_e32 v132, v77, v132
	v_sub_f32_e32 v2, v182, v133
	v_exp_f32_e32 v82, v82
	v_add_f32_e32 v132, v78, v132
	v_mul_f32_e32 v2, 0x3e0293ee, v2
	v_add_f32_e32 v132, v79, v132
	v_exp_f32_e32 v2, v2
	v_add_f32_e32 v132, v80, v132
	v_add_f32_e32 v132, v81, v132
	v_add_f32_e32 v132, v82, v132
	v_add_f32_e32 v149, v99, v132
	v_cndmask_b32_e64 v2, v2, 1.0, vcc
	v_mov_b32_e32 v150, v149
	v_cvt_pk_bf16_f32 v132, v83, v84
	v_cvt_pk_bf16_f32 v133, v85, v86
	v_cvt_pk_bf16_f32 v134, v87, v88
	v_cvt_pk_bf16_f32 v135, v89, v90
	v_cvt_pk_bf16_f32 v136, v91, v92
	v_cvt_pk_bf16_f32 v137, v93, v94
	v_cvt_pk_bf16_f32 v138, v95, v96
	v_cvt_pk_bf16_f32 v139, v97, v98
	v_cvt_pk_bf16_f32 v140, v68, v69
	v_cvt_pk_bf16_f32 v141, v70, v71
	v_cvt_pk_bf16_f32 v142, v72, v73
	v_cvt_pk_bf16_f32 v143, v74, v75
	v_cvt_pk_bf16_f32 v144, v76, v77
	v_cvt_pk_bf16_f32 v145, v78, v79
	v_cvt_pk_bf16_f32 v146, v80, v81
	v_cvt_pk_bf16_f32 v147, v82, v99
	s_nop 1
	v_permlane32_swap_b32_e32 v149, v150
	v_cmp_gt_f32_e32 vcc, 1.0, v2
	s_cbranch_vccz .LBB0_641
	s_and_saveexec_b64 s[16:17], s[38:39]
	ds_write_b32 v172, v2 offset:128
	s_or_b64 exec, exec, s[16:17]
	s_waitcnt lgkmcnt(0)
	v_add_u32_e32 v80, v171, v168
	ds_read_b128 v[68:71], v80 offset:224
	ds_read_b128 v[72:75], v80 offset:192
	ds_read_b128 v[76:79], v80 offset:160
	ds_read_b128 v[80:83], v80 offset:128
	s_waitcnt lgkmcnt(3)
	v_pk_mul_f32 v[16:17], v[16:17], v[68:69]
	s_waitcnt lgkmcnt(2)
	v_pk_mul_f32 v[12:13], v[12:13], v[72:73]
	s_waitcnt lgkmcnt(1)
	v_pk_mul_f32 v[8:9], v[8:9], v[76:77]
	v_pk_mul_f32 v[18:19], v[18:19], v[70:71]
	v_pk_mul_f32 v[14:15], v[14:15], v[74:75]
	v_pk_mul_f32 v[10:11], v[10:11], v[78:79]
	s_waitcnt lgkmcnt(0)
	v_pk_mul_f32 v[6:7], v[6:7], v[82:83]
	v_pk_mul_f32 v[4:5], v[4:5], v[80:81]
	v_pk_mul_f32 v[64:65], v[64:65], v[68:69]
	v_pk_mul_f32 v[60:61], v[60:61], v[72:73]
	v_pk_mul_f32 v[56:57], v[56:57], v[76:77]
	v_pk_mul_f32 v[66:67], v[66:67], v[70:71]
	v_pk_mul_f32 v[62:63], v[62:63], v[74:75]
	v_pk_mul_f32 v[58:59], v[58:59], v[78:79]
	v_pk_mul_f32 v[54:55], v[54:55], v[82:83]
	v_pk_mul_f32 v[52:53], v[52:53], v[80:81]
	v_pk_mul_f32 v[48:49], v[48:49], v[68:69]
	v_pk_mul_f32 v[44:45], v[44:45], v[72:73]
	v_pk_mul_f32 v[40:41], v[40:41], v[76:77]
	v_pk_mul_f32 v[50:51], v[50:51], v[70:71]
	v_pk_mul_f32 v[46:47], v[46:47], v[74:75]
	v_pk_mul_f32 v[42:43], v[42:43], v[78:79]
	v_pk_mul_f32 v[38:39], v[38:39], v[82:83]
	v_pk_mul_f32 v[36:37], v[36:37], v[80:81]
	v_pk_mul_f32 v[32:33], v[32:33], v[68:69]
	v_pk_mul_f32 v[28:29], v[28:29], v[72:73]
	v_pk_mul_f32 v[24:25], v[24:25], v[76:77]
	v_pk_mul_f32 v[34:35], v[34:35], v[70:71]
	v_pk_mul_f32 v[30:31], v[30:31], v[74:75]
	v_pk_mul_f32 v[26:27], v[26:27], v[78:79]
	v_pk_mul_f32 v[22:23], v[22:23], v[82:83]
	v_pk_mul_f32 v[20:21], v[20:21], v[80:81]
.LBB0_641:
	s_waitcnt lgkmcnt(0)
	s_barrier
	v_add_u32_e32 v202, s52, v173
	ds_read_b64_tr_b16 v[152:153], v202 offset:0
	ds_read_b64_tr_b16 v[154:155], v202 offset:0x800
	ds_read_b64_tr_b16 v[156:157], v202 offset:0x1000
	ds_read_b64_tr_b16 v[158:159], v202 offset:0x1800
	ds_read_b64_tr_b16 v[160:161], v202 offset:0x2000
	ds_read_b64_tr_b16 v[162:163], v202 offset:0x2800
	ds_read_b64_tr_b16 v[178:179], v202 offset:0x3000
	ds_read_b64_tr_b16 v[180:181], v202 offset:0x3800
	v_add_u32_e32 v203, s19, v174
	ds_read_b128 v[68:71], v203 offset:0
	ds_read_b128 v[72:75], v203 offset:0x2000
	v_add_u32_e32 v204, s19, v175
	v_add_u32_e32 v205, s19, v176
	v_add_u32_e32 v206, s19, v177
	ds_read_b128 v[174:177], v204 offset:0
	ds_read_b128 v[182:185], v204 offset:0x2000
	ds_read_b128 v[186:189], v205 offset:0
	ds_read_b128 v[190:193], v205 offset:0x2000
	ds_read_b128 v[194:197], v206 offset:0
	ds_read_b128 v[198:201], v206 offset:0x2000
	s_waitcnt lgkmcnt(4)
	v_mfma_f32_32x32x16_bf16 v[84:99], v[68:71], v[128:131], 0
	v_mfma_f32_32x32x16_bf16 v[68:83], v[72:75], v[128:131], 0
	v_mfma_f32_32x32x16_bf16 v[84:99], v[174:177], v[124:127], v[84:99]
	v_mfma_f32_32x32x16_bf16 v[68:83], v[182:185], v[124:127], v[68:83]
	ds_read_b128 v[124:127], v203 offset:0x80
	ds_read_b128 v[128:131], v203 offset:0x2080
	ds_read_b128 v[174:177], v204 offset:0x80
	ds_read_b128 v[182:185], v204 offset:0x2080
	s_waitcnt lgkmcnt(4)
	v_mfma_f32_32x32x16_bf16 v[84:99], v[186:189], v[120:123], v[84:99]
	v_mfma_f32_32x32x16_bf16 v[68:83], v[190:193], v[120:123], v[68:83]
	v_mfma_f32_32x32x16_bf16 v[84:99], v[194:197], v[116:119], v[84:99]
	v_mfma_f32_32x32x16_bf16 v[68:83], v[198:201], v[116:119], v[68:83]
	ds_read_b128 v[116:119], v205 offset:0x80
	ds_read_b128 v[120:123], v205 offset:0x2080
	ds_read_b128 v[186:189], v206 offset:0x80
	ds_read_b128 v[190:193], v206 offset:0x2080
	s_waitcnt lgkmcnt(4)
	v_mfma_f32_32x32x16_bf16 v[84:99], v[124:127], v[112:115], v[84:99]
	v_mfma_f32_32x32x16_bf16 v[68:83], v[128:131], v[112:115], v[68:83]
	v_mfma_f32_32x32x16_bf16 v[84:99], v[174:177], v[108:111], v[84:99]
	v_mfma_f32_32x32x16_bf16 v[68:83], v[182:185], v[108:111], v[68:83]
	s_waitcnt lgkmcnt(0)
	v_mfma_f32_32x32x16_bf16 v[84:99], v[116:119], v[104:107], v[84:99]
	v_mfma_f32_32x32x16_bf16 v[68:83], v[120:123], v[104:107], v[68:83]
	v_mfma_f32_32x32x16_bf16 v[84:99], v[186:189], v[100:103], v[84:99]
	v_mfma_f32_32x32x16_bf16 v[68:83], v[190:193], v[100:103], v[68:83]
	ds_read_b64_tr_b16 v[100:101], v202 offset:0x200
	ds_read_b64_tr_b16 v[102:103], v202 offset:0xa00
	ds_read_b64_tr_b16 v[104:105], v202 offset:0x1200
	ds_read_b64_tr_b16 v[106:107], v202 offset:0x1a00
	ds_read_b64_tr_b16 v[108:109], v202 offset:0x2200
	ds_read_b64_tr_b16 v[110:111], v202 offset:0x2a00
	ds_read_b64_tr_b16 v[112:113], v202 offset:0x3200
	ds_read_b64_tr_b16 v[114:115], v202 offset:0x3a00
	s_waitcnt lgkmcnt(8)
	v_mfma_f32_32x32x16_bf16 v[4:19], v[132:135], v[152:155], v[4:19]
	v_mfma_f32_32x32x16_bf16 v[4:19], v[136:139], v[156:159], v[4:19]
	v_mfma_f32_32x32x16_bf16 v[4:19], v[140:143], v[160:163], v[4:19]
	v_mfma_f32_32x32x16_bf16 v[4:19], v[144:147], v[178:181], v[4:19]
	ds_read_b64_tr_b16 v[116:117], v202 offset:0x400
	ds_read_b64_tr_b16 v[118:119], v202 offset:0xc00
	ds_read_b64_tr_b16 v[120:121], v202 offset:0x1400
	ds_read_b64_tr_b16 v[122:123], v202 offset:0x1c00
	ds_read_b64_tr_b16 v[124:125], v202 offset:0x2400
	ds_read_b64_tr_b16 v[126:127], v202 offset:0x2c00
	ds_read_b64_tr_b16 v[128:129], v202 offset:0x3400
	ds_read_b64_tr_b16 v[130:131], v202 offset:0x3c00
	s_waitcnt lgkmcnt(8)
	v_mfma_f32_32x32x16_bf16 v[52:67], v[132:135], v[100:103], v[52:67]
	v_mfma_f32_32x32x16_bf16 v[52:67], v[136:139], v[104:107], v[52:67]
	v_mfma_f32_32x32x16_bf16 v[52:67], v[140:143], v[108:111], v[52:67]
	v_mfma_f32_32x32x16_bf16 v[52:67], v[144:147], v[112:115], v[52:67]
	ds_read_b64_tr_b16 v[100:101], v202 offset:0x600
	ds_read_b64_tr_b16 v[102:103], v202 offset:0xe00
	ds_read_b64_tr_b16 v[104:105], v202 offset:0x1600
	ds_read_b64_tr_b16 v[106:107], v202 offset:0x1e00
	ds_read_b64_tr_b16 v[108:109], v202 offset:0x2600
	ds_read_b64_tr_b16 v[110:111], v202 offset:0x2e00
	ds_read_b64_tr_b16 v[112:113], v202 offset:0x3600
	ds_read_b64_tr_b16 v[114:115], v202 offset:0x3e00
	s_waitcnt lgkmcnt(8)
	v_mfma_f32_32x32x16_bf16 v[36:51], v[132:135], v[116:119], v[36:51]
	v_mfma_f32_32x32x16_bf16 v[36:51], v[136:139], v[120:123], v[36:51]
	v_mfma_f32_32x32x16_bf16 v[36:51], v[140:143], v[124:127], v[36:51]
	v_mfma_f32_32x32x16_bf16 v[36:51], v[144:147], v[128:131], v[36:51]
	s_waitcnt lgkmcnt(0)
	v_mfma_f32_32x32x16_bf16 v[20:35], v[132:135], v[100:103], v[20:35]
	v_mfma_f32_32x32x16_bf16 v[20:35], v[136:139], v[104:107], v[20:35]
	v_mfma_f32_32x32x16_bf16 v[20:35], v[140:143], v[108:111], v[20:35]
	v_mfma_f32_32x32x16_bf16 v[20:35], v[144:147], v[112:115], v[20:35]
	s_waitcnt lgkmcnt(0)
	s_barrier
	v_max_f32_e32 v100, v85, v85
	v_max_f32_e32 v101, v84, v84
	v_max_f32_e32 v100, v101, v100
	v_max3_f32 v100, v100, v86, v87
	v_max3_f32 v100, v100, v88, v89
	v_max3_f32 v100, v100, v90, v91
	v_max3_f32 v100, v100, v92, v93
	v_max3_f32 v100, v100, v94, v95
	v_max3_f32 v100, v100, v96, v97
	v_max3_f32 v100, v100, v98, v99
	v_max3_f32 v100, v100, v68, v69
	v_max3_f32 v100, v100, v70, v71
	v_max3_f32 v100, v100, v72, v73
	v_max3_f32 v100, v100, v74, v75
	v_max3_f32 v100, v100, v76, v77
	v_max3_f32 v100, v100, v78, v79
	v_max3_f32 v100, v100, v80, v81
	v_max3_f32 v100, v100, v82, v83
	v_mov_b32_e32 v101, v100
	s_nop 1
	v_permlane32_swap_b32_e32 v100, v101
	v_max_f32_e32 v101, v101, v101
	v_max_f32_e32 v100, v100, v100
	v_max_f32_e32 v100, v100, v101
	v_sub_f32_e32 v101, v100, v151
	v_cmp_ge_f32_e32 vcc, s23, v101
	s_cmp_eq_u64 vcc, exec
	v_max_f32_e32 v101, v151, v151
	s_cselect_b64 vcc, -1, 0
	v_max_f32_e32 v101, v101, v100
	v_sub_f32_e32 v100, v151, v101
	v_cndmask_b32_e32 v101, v101, v151, vcc
	v_mul_f32_e32 v101, 0xbe0293ee, v101
	v_fmamk_f32 v84, v84, 0x3e0293ee, v101
	v_fmamk_f32 v85, v85, 0x3e0293ee, v101
	v_fmamk_f32 v86, v86, 0x3e0293ee, v101
	v_fmamk_f32 v87, v87, 0x3e0293ee, v101
	v_fmamk_f32 v88, v88, 0x3e0293ee, v101
	v_fmamk_f32 v89, v89, 0x3e0293ee, v101
	v_fmamk_f32 v90, v90, 0x3e0293ee, v101
	v_fmamk_f32 v91, v91, 0x3e0293ee, v101
	v_fmamk_f32 v92, v92, 0x3e0293ee, v101
	v_fmamk_f32 v93, v93, 0x3e0293ee, v101
	v_fmamk_f32 v94, v94, 0x3e0293ee, v101
	v_fmamk_f32 v95, v95, 0x3e0293ee, v101
	v_fmamk_f32 v96, v96, 0x3e0293ee, v101
	v_fmamk_f32 v97, v97, 0x3e0293ee, v101
	v_fmamk_f32 v98, v98, 0x3e0293ee, v101
	v_fmamk_f32 v99, v99, 0x3e0293ee, v101
	v_fmamk_f32 v68, v68, 0x3e0293ee, v101
	v_fmamk_f32 v69, v69, 0x3e0293ee, v101
	v_fmamk_f32 v70, v70, 0x3e0293ee, v101
	v_fmamk_f32 v71, v71, 0x3e0293ee, v101
	v_fmamk_f32 v72, v72, 0x3e0293ee, v101
	v_fmamk_f32 v73, v73, 0x3e0293ee, v101
	v_fmamk_f32 v74, v74, 0x3e0293ee, v101
	v_fmamk_f32 v75, v75, 0x3e0293ee, v101
	v_fmamk_f32 v76, v76, 0x3e0293ee, v101
	v_fmamk_f32 v77, v77, 0x3e0293ee, v101
	v_fmamk_f32 v78, v78, 0x3e0293ee, v101
	v_fmamk_f32 v79, v79, 0x3e0293ee, v101
	v_fmamk_f32 v80, v80, 0x3e0293ee, v101
	v_fmamk_f32 v81, v81, 0x3e0293ee, v101
	v_fmamk_f32 v82, v82, 0x3e0293ee, v101
	v_fmac_f32_e32 v101, 0x3e0293ee, v83
	v_exp_f32_e32 v83, v84
	v_exp_f32_e32 v102, v85
	v_exp_f32_e32 v86, v86
	v_exp_f32_e32 v87, v87
	v_exp_f32_e32 v88, v88
	v_exp_f32_e32 v103, v68
	v_add_f32_e32 v68, 0, v83
	v_exp_f32_e32 v89, v89
	v_add_f32_e32 v68, v102, v68
	v_exp_f32_e32 v90, v90
	v_add_f32_e32 v68, v86, v68
	v_exp_f32_e32 v91, v91
	v_add_f32_e32 v68, v87, v68
	v_exp_f32_e32 v92, v92
	v_add_f32_e32 v68, v88, v68
	v_exp_f32_e32 v93, v93
	v_add_f32_e32 v68, v89, v68
	v_exp_f32_e32 v94, v94
	v_add_f32_e32 v68, v90, v68
	v_exp_f32_e32 v95, v95
	v_add_f32_e32 v68, v91, v68
	v_exp_f32_e32 v96, v96
	v_add_f32_e32 v68, v92, v68
	v_exp_f32_e32 v97, v97
	v_add_f32_e32 v68, v93, v68
	v_exp_f32_e32 v98, v98
	v_add_f32_e32 v68, v94, v68
	v_exp_f32_e32 v99, v99
	v_add_f32_e32 v68, v95, v68
	v_add_f32_e32 v68, v96, v68
	v_exp_f32_e32 v104, v69
	v_add_f32_e32 v68, v97, v68
	v_exp_f32_e32 v105, v70
	v_add_f32_e32 v68, v98, v68
	v_exp_f32_e32 v106, v71
	v_add_f32_e32 v68, v99, v68
	v_exp_f32_e32 v107, v72
	v_add_f32_e32 v68, v103, v68
	v_exp_f32_e32 v108, v73
	v_add_f32_e32 v68, v104, v68
	v_exp_f32_e32 v109, v74
	v_add_f32_e32 v68, v105, v68
	v_exp_f32_e32 v110, v75
	v_add_f32_e32 v68, v106, v68
	v_exp_f32_e32 v111, v76
	v_add_f32_e32 v68, v107, v68
	v_exp_f32_e32 v112, v77
	v_add_f32_e32 v68, v108, v68
	v_exp_f32_e32 v113, v78
	v_add_f32_e32 v68, v109, v68
	v_exp_f32_e32 v114, v79
	v_add_f32_e32 v68, v110, v68
	v_exp_f32_e32 v115, v80
	v_add_f32_e32 v68, v111, v68
	v_exp_f32_e32 v116, v81
	v_add_f32_e32 v68, v112, v68
	v_exp_f32_e32 v117, v82
	v_add_f32_e32 v68, v113, v68
	v_mul_f32_e32 v100, 0x3e0293ee, v100
	v_exp_f32_e32 v101, v101
	v_add_f32_e32 v68, v114, v68
	v_exp_f32_e32 v100, v100
	v_add_f32_e32 v68, v115, v68
	v_add_f32_e32 v68, v116, v68
	v_add_f32_e32 v68, v117, v68
	v_add_f32_e32 v84, v101, v68
	v_cndmask_b32_e64 v100, v100, 1.0, vcc
	v_mov_b32_e32 v85, v84
	v_cvt_pk_bf16_f32 v68, v83, v102
	v_cvt_pk_bf16_f32 v69, v86, v87
	v_cvt_pk_bf16_f32 v70, v88, v89
	v_cvt_pk_bf16_f32 v71, v90, v91
	v_cvt_pk_bf16_f32 v72, v92, v93
	v_cvt_pk_bf16_f32 v73, v94, v95
	v_cvt_pk_bf16_f32 v74, v96, v97
	v_cvt_pk_bf16_f32 v75, v98, v99
	v_cvt_pk_bf16_f32 v76, v103, v104
	v_cvt_pk_bf16_f32 v77, v105, v106
	v_cvt_pk_bf16_f32 v78, v107, v108
	v_cvt_pk_bf16_f32 v79, v109, v110
	v_cvt_pk_bf16_f32 v80, v111, v112
	v_cvt_pk_bf16_f32 v81, v113, v114
	v_cvt_pk_bf16_f32 v82, v115, v116
	v_cvt_pk_bf16_f32 v83, v117, v101
	s_nop 1
	v_permlane32_swap_b32_e32 v84, v85
	v_cmp_gt_f32_e32 vcc, 1.0, v100
	s_cbranch_vccz .LBB0_645
	s_and_saveexec_b64 s[16:17], s[38:39]
	ds_write_b32 v172, v100 offset:128
	s_or_b64 exec, exec, s[16:17]
	s_waitcnt lgkmcnt(0)
	v_add_u32_e32 v98, v171, v168
	ds_read_b128 v[86:89], v98 offset:224
	ds_read_b128 v[90:93], v98 offset:192
	ds_read_b128 v[94:97], v98 offset:160
	ds_read_b128 v[102:105], v98 offset:128
	s_waitcnt lgkmcnt(3)
	v_pk_mul_f32 v[16:17], v[16:17], v[86:87]
	s_waitcnt lgkmcnt(2)
	v_pk_mul_f32 v[12:13], v[12:13], v[90:91]
	s_waitcnt lgkmcnt(1)
	v_pk_mul_f32 v[8:9], v[8:9], v[94:95]
	v_pk_mul_f32 v[18:19], v[18:19], v[88:89]
	v_pk_mul_f32 v[14:15], v[14:15], v[92:93]
	v_pk_mul_f32 v[10:11], v[10:11], v[96:97]
	s_waitcnt lgkmcnt(0)
	v_pk_mul_f32 v[6:7], v[6:7], v[104:105]
	v_pk_mul_f32 v[4:5], v[4:5], v[102:103]
	v_pk_mul_f32 v[64:65], v[64:65], v[86:87]
	v_pk_mul_f32 v[60:61], v[60:61], v[90:91]
	v_pk_mul_f32 v[56:57], v[56:57], v[94:95]
	v_pk_mul_f32 v[66:67], v[66:67], v[88:89]
	v_pk_mul_f32 v[62:63], v[62:63], v[92:93]
	v_pk_mul_f32 v[58:59], v[58:59], v[96:97]
	v_pk_mul_f32 v[54:55], v[54:55], v[104:105]
	v_pk_mul_f32 v[52:53], v[52:53], v[102:103]
	v_pk_mul_f32 v[48:49], v[48:49], v[86:87]
	v_pk_mul_f32 v[44:45], v[44:45], v[90:91]
	v_pk_mul_f32 v[40:41], v[40:41], v[94:95]
	v_pk_mul_f32 v[50:51], v[50:51], v[88:89]
	v_pk_mul_f32 v[46:47], v[46:47], v[92:93]
	v_pk_mul_f32 v[42:43], v[42:43], v[96:97]
	v_pk_mul_f32 v[38:39], v[38:39], v[104:105]
	v_pk_mul_f32 v[36:37], v[36:37], v[102:103]
	v_pk_mul_f32 v[32:33], v[32:33], v[86:87]
	v_pk_mul_f32 v[28:29], v[28:29], v[90:91]
	v_pk_mul_f32 v[24:25], v[24:25], v[94:95]
	v_pk_mul_f32 v[34:35], v[34:35], v[88:89]
	v_pk_mul_f32 v[30:31], v[30:31], v[92:93]
	v_pk_mul_f32 v[26:27], v[26:27], v[96:97]
	v_pk_mul_f32 v[22:23], v[22:23], v[104:105]
	v_pk_mul_f32 v[20:21], v[20:21], v[102:103]
